# R1 state stores widened: adjacent dk blocks paired with v_permlane16_swap, eight 16-byte stores per direction instead of sixteen 8-byte ones
# speedup vs baseline: 1.0023x; 1.0023x over previous
.LBB0_957:
	s_and_b32 s0, s3, 3
	s_and_b32 s3, s48, 7
	s_lshl_b32 s10, s43, 4
	s_or_b32 s10, s10, s3
	s_ashr_i32 s11, s10, 31
	s_lshl_b64 s[12:13], s[10:11], 17
	v_lshl_or_b32 v104, s0, 15, v235
	v_mov_b32_e32 v105, v145
	v_lshl_add_u64 v[106:107], v[168:169], 0, s[12:13]
	v_lshl_add_u64 v[106:107], v[106:107], 0, v[104:105]
	v_bfe_u32 v108, v230, 4, 1
	v_mul_u32_u24_e32 v108, 24, v108
	v_mov_b32_e32 v109, v145
	v_lshl_add_u64 v[106:107], v[106:107], 0, v[108:109]
	s_or_b32 s10, s10, 8
	s_ashr_i32 s11, s10, 31
	s_lshl_b64 s[10:11], s[10:11], 17
	v_lshl_add_u64 v[110:111], v[168:169], 0, s[10:11]
	v_lshl_add_u64 v[110:111], v[110:111], 0, v[104:105]
	v_lshl_add_u64 v[110:111], v[110:111], 0, v[108:109]
	v_cvt_pk_bf16_f32 v112, v100, v101
	v_cvt_pk_bf16_f32 v113, v102, v103
	v_cvt_pk_bf16_f32 v114, v96, v97
	v_cvt_pk_bf16_f32 v115, v98, v99
	s_nop 1
	v_permlane16_swap_b32_e32 v112, v114
	v_permlane16_swap_b32_e32 v113, v115
	s_nop 1
	global_store_dwordx4 v[106:107], v[112:115], off
	v_cvt_pk_bf16_f32 v116, v88, v89
	v_cvt_pk_bf16_f32 v117, v90, v91
	v_cvt_pk_bf16_f32 v118, v80, v81
	v_cvt_pk_bf16_f32 v119, v82, v83
	s_nop 1
	v_permlane16_swap_b32_e32 v116, v118
	v_permlane16_swap_b32_e32 v117, v119
	s_nop 1
	global_store_dwordx4 v[106:107], v[116:119], off offset:64
	v_cvt_pk_bf16_f32 v112, v92, v93
	v_cvt_pk_bf16_f32 v113, v94, v95
	v_cvt_pk_bf16_f32 v114, v84, v85
	v_cvt_pk_bf16_f32 v115, v86, v87
	s_nop 1
	v_permlane16_swap_b32_e32 v112, v114
	v_permlane16_swap_b32_e32 v113, v115
	s_nop 1
	global_store_dwordx4 v[106:107], v[112:115], off offset:128
	v_cvt_pk_bf16_f32 v116, v76, v77
	v_cvt_pk_bf16_f32 v117, v78, v79
	v_cvt_pk_bf16_f32 v118, v72, v73
	v_cvt_pk_bf16_f32 v119, v74, v75
	s_nop 1
	v_permlane16_swap_b32_e32 v116, v118
	v_permlane16_swap_b32_e32 v117, v119
	s_nop 1
	global_store_dwordx4 v[106:107], v[116:119], off offset:192
	v_cvt_pk_bf16_f32 v112, v68, v69
	v_cvt_pk_bf16_f32 v113, v70, v71
	v_cvt_pk_bf16_f32 v114, v64, v65
	v_cvt_pk_bf16_f32 v115, v66, v67
	s_nop 1
	v_permlane16_swap_b32_e32 v112, v114
	v_permlane16_swap_b32_e32 v113, v115
	s_nop 1
	global_store_dwordx4 v[110:111], v[112:115], off
	v_cvt_pk_bf16_f32 v116, v56, v57
	v_cvt_pk_bf16_f32 v117, v58, v59
	v_cvt_pk_bf16_f32 v118, v52, v53
	v_cvt_pk_bf16_f32 v119, v54, v55
	s_nop 1
	v_permlane16_swap_b32_e32 v116, v118
	v_permlane16_swap_b32_e32 v117, v119
	s_nop 1
	global_store_dwordx4 v[110:111], v[116:119], off offset:64
	v_cvt_pk_bf16_f32 v112, v60, v61
	v_cvt_pk_bf16_f32 v113, v62, v63
	v_cvt_pk_bf16_f32 v114, v48, v49
	v_cvt_pk_bf16_f32 v115, v50, v51
	s_nop 1
	v_permlane16_swap_b32_e32 v112, v114
	v_permlane16_swap_b32_e32 v113, v115
	s_nop 1
	global_store_dwordx4 v[110:111], v[112:115], off offset:128
	v_cvt_pk_bf16_f32 v116, v44, v45
	v_cvt_pk_bf16_f32 v117, v46, v47
	v_cvt_pk_bf16_f32 v118, v40, v41
	v_cvt_pk_bf16_f32 v119, v42, v43
	s_nop 1
	v_permlane16_swap_b32_e32 v116, v118
	v_permlane16_swap_b32_e32 v117, v119
	s_nop 1
	global_store_dwordx4 v[110:111], v[116:119], off offset:192
	s_add_i32 s42, s42, s30
	s_and_b64 vcc, exec, s[8:9]
	s_mov_b32 s3, s49
	s_cbranch_vccnz .LBB0_967
